# XCD-local barriers polling the arrival counter; the last arriver waits vmcnt(1) so its L1 invalidate has completed before the closing barrier
# baseline (speedup 1.0000x reference)
.Lloc_d:
	v_readlane_b32 s2, v252, 49
	v_readlane_b32 s3, v252, 50
	s_waitcnt vmcnt(0)
	buffer_inv sc1
	s_nop 2
	global_atomic_add v197, v223, s[2:3]
	s_waitcnt vmcnt(1)
	s_branch .LBB0_125
